# layer 0: residual stream read from x at the first output projection, h = x copy dropped
# speedup vs baseline: 1.0059x; 1.0059x over previous
.LBB0_675:
	s_load_dwordx2 s[16:17], s[0:1], 0x148
	s_waitcnt lgkmcnt(0)
	v_lshl_add_u64 v[0:1], s[6:7], 0, v[38:39]
	v_lshl_add_u64 v[4:5], s[16:17], 0, v[38:39]
	v_add_u32_e32 v32, s8, v32
	v_add_co_u32_e32 v2, vcc, 0xfffff000, v0
	s_nop 1
	v_addc_co_u32_e32 v3, vcc, -1, v1, vcc
	global_load_dwordx4 v[56:59], v[2:3], off offset:-3072
	global_load_dwordx4 v[60:63], v[2:3], off offset:-2048
	global_load_dwordx4 v[64:67], v[2:3], off offset:-1024
	global_load_dwordx4 v[68:71], v[0:1], off offset:-4096
	global_load_dwordx4 v[72:75], v[0:1], off offset:-3072
	global_load_dwordx4 v[76:79], v[0:1], off offset:-2048
	global_load_dwordx4 v[80:83], v[0:1], off offset:-1024
	global_load_dwordx4 v[84:87], v[0:1], off
	v_add_co_u32_e32 v6, vcc, 0xfffff000, v4
	s_nop 1
	v_addc_co_u32_e32 v7, vcc, -1, v5, vcc
	v_lshl_add_u64 v[38:39], v[38:39], 0, s[12:13]
	v_cmp_lt_i32_e32 vcc, s74, v32
	s_or_b64 s[14:15], vcc, s[14:15]
	s_waitcnt vmcnt(0)
	v_mul_f32_e32 v121, v57, v57
	v_mul_f32_e32 v122, v59, v59
	v_fma_f32 v121, v56, v56, v121
	v_fma_f32 v122, v58, v58, v122
	v_add_f32_e32 v121, v121, v122
	v_mov_b32_e32 v120, v121
	v_mul_f32_e32 v121, v61, v61
	v_mul_f32_e32 v122, v63, v63
	v_fma_f32 v121, v60, v60, v121
	v_fma_f32 v122, v62, v62, v122
	v_add_f32_e32 v121, v121, v122
	v_add_f32_e32 v120, v120, v121
	v_mul_f32_e32 v121, v65, v65
	v_mul_f32_e32 v122, v67, v67
	v_fma_f32 v121, v64, v64, v121
	v_fma_f32 v122, v66, v66, v122
	v_add_f32_e32 v121, v121, v122
	v_add_f32_e32 v120, v120, v121
	v_mul_f32_e32 v121, v69, v69
	v_mul_f32_e32 v122, v71, v71
	v_fma_f32 v121, v68, v68, v121
	v_fma_f32 v122, v70, v70, v122
	v_add_f32_e32 v121, v121, v122
	v_add_f32_e32 v120, v120, v121
	v_mul_f32_e32 v121, v73, v73
	v_mul_f32_e32 v122, v75, v75
	v_fma_f32 v121, v72, v72, v121
	v_fma_f32 v122, v74, v74, v122
	v_add_f32_e32 v121, v121, v122
	v_add_f32_e32 v120, v120, v121
	v_mul_f32_e32 v121, v77, v77
	v_mul_f32_e32 v122, v79, v79
	v_fma_f32 v121, v76, v76, v121
	v_fma_f32 v122, v78, v78, v122
	v_add_f32_e32 v121, v121, v122
	v_add_f32_e32 v120, v120, v121
	v_mul_f32_e32 v121, v81, v81
	v_mul_f32_e32 v122, v83, v83
	v_fma_f32 v121, v80, v80, v121
	v_fma_f32 v122, v82, v82, v122
	v_add_f32_e32 v121, v121, v122
	v_add_f32_e32 v120, v120, v121
	v_mul_f32_e32 v121, v85, v85
	v_mul_f32_e32 v122, v87, v87
	v_fma_f32 v121, v84, v84, v121
	v_fma_f32 v122, v86, v86, v122
	v_add_f32_e32 v121, v121, v122
	v_add_f32_e32 v120, v120, v121
	s_nop 1
	v_add_f32_dpp v120, v120, v120 quad_perm:[1,0,3,2] row_mask:0xf bank_mask:0xf bound_ctrl:1
	s_nop 1
	v_add_f32_dpp v120, v120, v120 quad_perm:[2,3,0,1] row_mask:0xf bank_mask:0xf bound_ctrl:1
	s_nop 1
	v_add_f32_dpp v120, v120, v120 row_half_mirror row_mask:0xf bank_mask:0xf bound_ctrl:1
	s_nop 1
	v_add_f32_dpp v120, v120, v120 row_mirror row_mask:0xf bank_mask:0xf bound_ctrl:1
	s_nop 1
	v_readlane_b32 s2, v120, 16
	v_readlane_b32 s9, v120, 48
	v_readlane_b32 s18, v120, 0
	v_readlane_b32 s19, v120, 32
	v_mov_b32_e32 v122, s2
	v_mov_b32_e32 v123, s9
	v_pk_add_f32 v[122:123], s[18:19], v[122:123]
	s_nop 0
	v_add_f32_e32 v120, v122, v123
	v_fmamk_f32 v120, v120, 0x3a000000, v227
	v_cmp_gt_f32_e32 vcc, s29, v120
	v_mul_f32_e32 v121, 0x4b800000, v120
	s_nop 0
	v_cndmask_b32_e32 v120, v120, v121, vcc
	v_rsq_f32_e32 v120, v120
	s_nop 0
	v_mul_f32_e32 v121, 0x45800000, v120
	v_cndmask_b32_e32 v120, v120, v121, vcc
	v_pk_mul_f32 v[140:141], v[56:57], v[120:121] op_sel_hi:[1,0]
	v_pk_mul_f32 v[142:143], v[58:59], v[120:121] op_sel_hi:[1,0]
	v_pk_mul_f32 v[140:141], v[140:141], v[88:89]
	v_pk_mul_f32 v[142:143], v[142:143], v[90:91]
	v_cvt_pk_bf16_f32 v144, v140, v141
	v_cvt_pk_bf16_f32 v145, v142, v143
	global_store_dwordx2 v[36:37], v[144:145], off offset:-3584
	v_pk_mul_f32 v[146:147], v[60:61], v[120:121] op_sel_hi:[1,0]
	v_pk_mul_f32 v[148:149], v[62:63], v[120:121] op_sel_hi:[1,0]
	v_pk_mul_f32 v[146:147], v[146:147], v[92:93]
	v_pk_mul_f32 v[148:149], v[148:149], v[94:95]
	v_cvt_pk_bf16_f32 v150, v146, v147
	v_cvt_pk_bf16_f32 v151, v148, v149
	global_store_dwordx2 v[36:37], v[150:151], off offset:-3072
	v_pk_mul_f32 v[140:141], v[64:65], v[120:121] op_sel_hi:[1,0]
	v_pk_mul_f32 v[142:143], v[66:67], v[120:121] op_sel_hi:[1,0]
	v_pk_mul_f32 v[140:141], v[140:141], v[96:97]
	v_pk_mul_f32 v[142:143], v[142:143], v[98:99]
	v_cvt_pk_bf16_f32 v144, v140, v141
	v_cvt_pk_bf16_f32 v145, v142, v143
	global_store_dwordx2 v[36:37], v[144:145], off offset:-2560
	v_pk_mul_f32 v[146:147], v[68:69], v[120:121] op_sel_hi:[1,0]
	v_pk_mul_f32 v[148:149], v[70:71], v[120:121] op_sel_hi:[1,0]
	v_pk_mul_f32 v[146:147], v[146:147], v[100:101]
	v_pk_mul_f32 v[148:149], v[148:149], v[102:103]
	v_cvt_pk_bf16_f32 v150, v146, v147
	v_cvt_pk_bf16_f32 v151, v148, v149
	global_store_dwordx2 v[36:37], v[150:151], off offset:-2048
	v_pk_mul_f32 v[140:141], v[72:73], v[120:121] op_sel_hi:[1,0]
	v_pk_mul_f32 v[142:143], v[74:75], v[120:121] op_sel_hi:[1,0]
	v_pk_mul_f32 v[140:141], v[140:141], v[104:105]
	v_pk_mul_f32 v[142:143], v[142:143], v[106:107]
	v_cvt_pk_bf16_f32 v144, v140, v141
	v_cvt_pk_bf16_f32 v145, v142, v143
	global_store_dwordx2 v[36:37], v[144:145], off offset:-1536
	v_pk_mul_f32 v[146:147], v[76:77], v[120:121] op_sel_hi:[1,0]
	v_pk_mul_f32 v[148:149], v[78:79], v[120:121] op_sel_hi:[1,0]
	v_pk_mul_f32 v[146:147], v[146:147], v[108:109]
	v_pk_mul_f32 v[148:149], v[148:149], v[110:111]
	v_cvt_pk_bf16_f32 v150, v146, v147
	v_cvt_pk_bf16_f32 v151, v148, v149
	global_store_dwordx2 v[36:37], v[150:151], off offset:-1024
	v_pk_mul_f32 v[140:141], v[80:81], v[120:121] op_sel_hi:[1,0]
	v_pk_mul_f32 v[142:143], v[82:83], v[120:121] op_sel_hi:[1,0]
	v_pk_mul_f32 v[140:141], v[140:141], v[112:113]
	v_pk_mul_f32 v[142:143], v[142:143], v[114:115]
	v_cvt_pk_bf16_f32 v144, v140, v141
	v_cvt_pk_bf16_f32 v145, v142, v143
	global_store_dwordx2 v[36:37], v[144:145], off offset:-512
	v_pk_mul_f32 v[146:147], v[84:85], v[120:121] op_sel_hi:[1,0]
	v_pk_mul_f32 v[148:149], v[86:87], v[120:121] op_sel_hi:[1,0]
	v_pk_mul_f32 v[146:147], v[146:147], v[116:117]
	v_pk_mul_f32 v[148:149], v[148:149], v[118:119]
	v_cvt_pk_bf16_f32 v150, v146, v147
	v_cvt_pk_bf16_f32 v151, v148, v149
	global_store_dwordx2 v[36:37], v[150:151], off
	v_lshl_add_u64 v[36:37], v[36:37], 0, s[4:5]
	s_andn2_b64 exec, exec, s[14:15]
	s_cbranch_execnz .LBB0_675

.LBB0_772:
	s_and_b64 vcc, exec, s[4:5]
	s_cbranch_vccz .LBB0_774
	s_load_dwordx2 s[4:5], s[0:1], 0x148
	s_load_dwordx2 s[26:27], s[0:1], 0x0
	v_readlane_b32 s30, v255, 35
	v_readlane_b32 s31, v255, 49
	s_lshl_b32 s38, s70, 2
	v_lshlrev_b32_e32 v128, 2, v172
	v_mov_b32_e32 v129, v169
	s_waitcnt lgkmcnt(0)
	s_sub_u32 s26, s26, s4
	s_subb_u32 s27, s27, s5
	s_cmp_lg_u32 s30, 0
	s_cselect_b32 s26, 0, s26
	s_cselect_b32 s27, 0, s27
	s_cmp_lg_u32 s31, 7
	s_cselect_b32 s26, 0, s26
	s_cselect_b32 s27, 0, s27
	s_add_u32 s30, s4, s38
	s_addc_u32 s31, s5, 0
	v_lshl_add_u64 v[130:131], s[30:31], 0, v[128:129]
	s_lshl_b64 s[30:31], s[24:25], 2
	v_lshl_add_u64 v[130:131], v[130:131], 0, s[30:31]
	v_add_u32_e32 v250, s54, v192
	v_ashrrev_i32_e32 v251, 31, v250
	v_lshlrev_b64 v[250:251], 13, v[250:251]
	v_lshl_add_u64 v[164:165], v[130:131], 0, v[250:251]
	v_lshl_add_u64 v[190:191], v[164:165], 0, s[26:27]
	global_load_dwordx4 v[132:135], v[190:191], off
	global_load_dwordx4 v[136:139], v[190:191], off offset:64
	global_load_dwordx4 v[140:143], v[190:191], off offset:512
	global_load_dwordx4 v[144:147], v[190:191], off offset:576
	v_add_u32_e32 v250, s54, v194
	v_ashrrev_i32_e32 v251, 31, v250
	v_lshlrev_b64 v[250:251], 13, v[250:251]
	v_lshl_add_u64 v[166:167], v[130:131], 0, v[250:251]
	v_lshl_add_u64 v[190:191], v[166:167], 0, s[26:27]
	global_load_dwordx4 v[148:151], v[190:191], off
	global_load_dwordx4 v[152:155], v[190:191], off offset:64
	global_load_dwordx4 v[156:159], v[190:191], off offset:512
	global_load_dwordx4 v[160:163], v[190:191], off offset:576
	v_add_u32_e32 v250, s54, v195
	v_ashrrev_i32_e32 v251, 31, v250
	v_lshlrev_b64 v[250:251], 13, v[250:251]
	v_lshl_add_u64 v[224:225], v[130:131], 0, v[250:251]
	v_lshl_add_u64 v[190:191], v[224:225], 0, s[26:27]
	global_load_dwordx4 v[204:207], v[190:191], off
	global_load_dwordx4 v[208:211], v[190:191], off offset:64
	global_load_dwordx4 v[212:215], v[190:191], off offset:512
	global_load_dwordx4 v[216:219], v[190:191], off offset:576
	v_add_u32_e32 v250, s54, v196
	v_ashrrev_i32_e32 v251, 31, v250
	v_lshlrev_b64 v[250:251], 13, v[250:251]
	v_lshl_add_u64 v[248:249], v[130:131], 0, v[250:251]
	v_lshl_add_u64 v[190:191], v[248:249], 0, s[26:27]
	global_load_dwordx4 v[220:223], v[190:191], off
	global_load_dwordx4 v[232:235], v[190:191], off offset:64
	global_load_dwordx4 v[240:243], v[190:191], off offset:512
	global_load_dwordx4 v[244:247], v[190:191], off offset:576
	s_waitcnt vmcnt(8)
	v_pk_add_f32 v[132:133], v[124:125], v[132:133]
	v_pk_add_f32 v[134:135], v[126:127], v[134:135]
	global_store_dwordx4 v[164:165], v[132:135], off sc1
	v_pk_add_f32 v[136:137], v[120:121], v[136:137]
	v_pk_add_f32 v[138:139], v[122:123], v[138:139]
	global_store_dwordx4 v[164:165], v[136:139], off offset:64 sc1
	v_pk_add_f32 v[140:141], v[116:117], v[140:141]
	v_pk_add_f32 v[142:143], v[118:119], v[142:143]
	global_store_dwordx4 v[164:165], v[140:143], off offset:512 sc1
	v_pk_add_f32 v[144:145], v[112:113], v[144:145]
	v_pk_add_f32 v[146:147], v[114:115], v[146:147]
	global_store_dwordx4 v[164:165], v[144:147], off offset:576 sc1
	v_pk_add_f32 v[148:149], v[108:109], v[148:149]
	v_pk_add_f32 v[150:151], v[110:111], v[150:151]
	global_store_dwordx4 v[166:167], v[148:151], off sc1
	v_pk_add_f32 v[152:153], v[104:105], v[152:153]
	v_pk_add_f32 v[154:155], v[106:107], v[154:155]
	global_store_dwordx4 v[166:167], v[152:155], off offset:64 sc1
	v_pk_add_f32 v[156:157], v[100:101], v[156:157]
	v_pk_add_f32 v[158:159], v[102:103], v[158:159]
	global_store_dwordx4 v[166:167], v[156:159], off offset:512 sc1
	v_pk_add_f32 v[160:161], v[96:97], v[160:161]
	v_pk_add_f32 v[162:163], v[98:99], v[162:163]
	global_store_dwordx4 v[166:167], v[160:163], off offset:576 sc1
	s_nop 1
	v_add_u32_e32 v250, s54, v197
	v_ashrrev_i32_e32 v251, 31, v250
	v_lshlrev_b64 v[250:251], 13, v[250:251]
	v_lshl_add_u64 v[164:165], v[130:131], 0, v[250:251]
	v_lshl_add_u64 v[190:191], v[164:165], 0, s[26:27]
	global_load_dwordx4 v[132:135], v[190:191], off
	global_load_dwordx4 v[136:139], v[190:191], off offset:64
	global_load_dwordx4 v[140:143], v[190:191], off offset:512
	global_load_dwordx4 v[144:147], v[190:191], off offset:576
	v_add_u32_e32 v250, s54, v198
	v_ashrrev_i32_e32 v251, 31, v250
	v_lshlrev_b64 v[250:251], 13, v[250:251]
	v_lshl_add_u64 v[166:167], v[130:131], 0, v[250:251]
	v_lshl_add_u64 v[190:191], v[166:167], 0, s[26:27]
	global_load_dwordx4 v[148:151], v[190:191], off
	global_load_dwordx4 v[152:155], v[190:191], off offset:64
	global_load_dwordx4 v[156:159], v[190:191], off offset:512
	global_load_dwordx4 v[160:163], v[190:191], off offset:576
	s_waitcnt vmcnt(16)
	v_pk_add_f32 v[204:205], v[92:93], v[204:205]
	v_pk_add_f32 v[206:207], v[94:95], v[206:207]
	global_store_dwordx4 v[224:225], v[204:207], off sc1
	v_pk_add_f32 v[208:209], v[88:89], v[208:209]
	v_pk_add_f32 v[210:211], v[90:91], v[210:211]
	global_store_dwordx4 v[224:225], v[208:211], off offset:64 sc1
	v_pk_add_f32 v[212:213], v[84:85], v[212:213]
	v_pk_add_f32 v[214:215], v[86:87], v[214:215]
	global_store_dwordx4 v[224:225], v[212:215], off offset:512 sc1
	v_pk_add_f32 v[216:217], v[80:81], v[216:217]
	v_pk_add_f32 v[218:219], v[82:83], v[218:219]
	global_store_dwordx4 v[224:225], v[216:219], off offset:576 sc1
	v_pk_add_f32 v[220:221], v[76:77], v[220:221]
	v_pk_add_f32 v[222:223], v[78:79], v[222:223]
	global_store_dwordx4 v[248:249], v[220:223], off sc1
	v_pk_add_f32 v[232:233], v[72:73], v[232:233]
	v_pk_add_f32 v[234:235], v[74:75], v[234:235]
	global_store_dwordx4 v[248:249], v[232:235], off offset:64 sc1
	v_pk_add_f32 v[240:241], v[68:69], v[240:241]
	v_pk_add_f32 v[242:243], v[70:71], v[242:243]
	global_store_dwordx4 v[248:249], v[240:243], off offset:512 sc1
	v_pk_add_f32 v[244:245], v[64:65], v[244:245]
	v_pk_add_f32 v[246:247], v[66:67], v[246:247]
	global_store_dwordx4 v[248:249], v[244:247], off offset:576 sc1
	s_nop 1
	v_add_u32_e32 v250, s54, v199
	v_ashrrev_i32_e32 v251, 31, v250
	v_lshlrev_b64 v[250:251], 13, v[250:251]
	v_lshl_add_u64 v[224:225], v[130:131], 0, v[250:251]
	v_lshl_add_u64 v[190:191], v[224:225], 0, s[26:27]
	global_load_dwordx4 v[204:207], v[190:191], off
	global_load_dwordx4 v[208:211], v[190:191], off offset:64
	global_load_dwordx4 v[212:215], v[190:191], off offset:512
	global_load_dwordx4 v[216:219], v[190:191], off offset:576
	v_add_u32_e32 v250, s54, v200
	v_ashrrev_i32_e32 v251, 31, v250
	v_lshlrev_b64 v[250:251], 13, v[250:251]
	v_lshl_add_u64 v[248:249], v[130:131], 0, v[250:251]
	v_lshl_add_u64 v[190:191], v[248:249], 0, s[26:27]
	global_load_dwordx4 v[220:223], v[190:191], off
	global_load_dwordx4 v[232:235], v[190:191], off offset:64
	global_load_dwordx4 v[240:243], v[190:191], off offset:512
	global_load_dwordx4 v[244:247], v[190:191], off offset:576
	s_waitcnt vmcnt(16)
	v_pk_add_f32 v[132:133], v[60:61], v[132:133]
	v_pk_add_f32 v[134:135], v[62:63], v[134:135]
	global_store_dwordx4 v[164:165], v[132:135], off sc1
	v_pk_add_f32 v[136:137], v[56:57], v[136:137]
	v_pk_add_f32 v[138:139], v[58:59], v[138:139]
	global_store_dwordx4 v[164:165], v[136:139], off offset:64 sc1
	v_pk_add_f32 v[140:141], v[52:53], v[140:141]
	v_pk_add_f32 v[142:143], v[54:55], v[142:143]
	global_store_dwordx4 v[164:165], v[140:143], off offset:512 sc1
	v_pk_add_f32 v[144:145], v[48:49], v[144:145]
	v_pk_add_f32 v[146:147], v[50:51], v[146:147]
	global_store_dwordx4 v[164:165], v[144:147], off offset:576 sc1
	v_pk_add_f32 v[148:149], v[44:45], v[148:149]
	v_pk_add_f32 v[150:151], v[46:47], v[150:151]
	global_store_dwordx4 v[166:167], v[148:151], off sc1
	v_pk_add_f32 v[152:153], v[40:41], v[152:153]
	v_pk_add_f32 v[154:155], v[42:43], v[154:155]
	global_store_dwordx4 v[166:167], v[152:155], off offset:64 sc1
	v_pk_add_f32 v[156:157], v[36:37], v[156:157]
	v_pk_add_f32 v[158:159], v[38:39], v[158:159]
	global_store_dwordx4 v[166:167], v[156:159], off offset:512 sc1
	v_pk_add_f32 v[160:161], v[32:33], v[160:161]
	v_pk_add_f32 v[162:163], v[34:35], v[162:163]
	global_store_dwordx4 v[166:167], v[160:163], off offset:576 sc1
	s_waitcnt vmcnt(8)
	v_pk_add_f32 v[204:205], v[28:29], v[204:205]
	v_pk_add_f32 v[206:207], v[30:31], v[206:207]
	global_store_dwordx4 v[224:225], v[204:207], off sc1
	v_pk_add_f32 v[208:209], v[24:25], v[208:209]
	v_pk_add_f32 v[210:211], v[26:27], v[210:211]
	global_store_dwordx4 v[224:225], v[208:211], off offset:64 sc1
	v_pk_add_f32 v[212:213], v[20:21], v[212:213]
	v_pk_add_f32 v[214:215], v[22:23], v[214:215]
	global_store_dwordx4 v[224:225], v[212:215], off offset:512 sc1
	v_pk_add_f32 v[216:217], v[16:17], v[216:217]
	v_pk_add_f32 v[218:219], v[18:19], v[218:219]
	global_store_dwordx4 v[224:225], v[216:219], off offset:576 sc1
	v_pk_add_f32 v[220:221], v[12:13], v[220:221]
	v_pk_add_f32 v[222:223], v[14:15], v[222:223]
	global_store_dwordx4 v[248:249], v[220:223], off sc1
	v_pk_add_f32 v[232:233], v[8:9], v[232:233]
	v_pk_add_f32 v[234:235], v[10:11], v[234:235]
	global_store_dwordx4 v[248:249], v[232:235], off offset:64 sc1
	v_pk_add_f32 v[240:241], v[4:5], v[240:241]
	v_pk_add_f32 v[242:243], v[6:7], v[242:243]
	global_store_dwordx4 v[248:249], v[240:243], off offset:512 sc1
	v_pk_add_f32 v[244:245], v[0:1], v[244:245]
	v_pk_add_f32 v[246:247], v[2:3], v[246:247]
	global_store_dwordx4 v[248:249], v[244:247], off offset:576 sc1
